# k24 stack + DSA gather tile loop unrolled x2 with two register sets (prefetch distance 2, counted vmcnt)
# speedup vs baseline: 1.0078x; 1.0078x over previous
; #define LAS __attribute__((address_space(3)))
; #define MFMA32(a, b, c) __builtin_amdgcn_mfma_f32_32x32x16_bf16((a), (b), (c), 0, 0, 0)
; DI float fexp2(float x) { return __builtin_amdgcn_exp2f(x); }
; DI f32x16 zero16() { f32x16 z; for (int i = 0; i < 16; ++i) z[i] = 0.f; return z; }
; DI void dsa_unit(const Params& p, int l, int b, int g32, LAS unsigned char* lds) {
;     ...
;     f32x16 o[2] = {zero16(), zero16()}; float lsum = 0.f;
;     u32x4 ka[4], va4[4];
;     {
;       const unsigned ik = cq[r] & 0x1FFFu; const u16* kp = kvc + ((size_t)b * S + ik) * 128 + 8 * h;
; #pragma unroll
;       for (int s = 0; s < 4; ++s) ka[s] = *(const u32x4*)(kp + 16 * s);
; #pragma unroll
;       for (int u = 0; u < 4; ++u) { const unsigned iv = cq[8 * u + ks] & 0x1FFFu; va4[u] = *(const u32x4*)(kvc + ((size_t)b * S + iv) * 128 + 64 + 8 * dg); }
;     }
;     const int ntile = nc >> 5;
; #pragma unroll 1
;     for (int mt = 0; mt < ntile; ++mt) {
;       bf16x8 a[4];
; #pragma unroll
;       for (int s = 0; s < 4; ++s) a[s] = __builtin_bit_cast(bf16x8, ka[s]);
; #pragma unroll
;       for (int u = 0; u < 4; ++u) *(LAS u32x4*)(vt + (8 * u + ks) * KT_RS + dg * 16) = va4[u];
;       if (mt + 1 < ntile) {
;         const unsigned ik = cq[32 * (mt + 1) + r] & 0x1FFFu; const u16* kp = kvc + ((size_t)b * S + ik) * 128 + 8 * h;
; #pragma unroll
;         for (int s = 0; s < 4; ++s) ka[s] = *(const u32x4*)(kp + 16 * s);
; #pragma unroll
;         for (int u = 0; u < 4; ++u) { const unsigned iv = cq[32 * (mt + 1) + 8 * u + ks] & 0x1FFFu; va4[u] = *(const u32x4*)(kvc + ((size_t)b * S + iv) * 128 + 64 + 8 * dg); }
;       }
;       f32x16 sc = zero16();
; #pragma unroll
;       for (int s = 0; s < 4; ++s) sc = MFMA32(a[s], qb[s], sc);
; #pragma unroll
;       for (int i = 0; i < 16; ++i) { sc[i] = fexp2(sc[i]); lsum += sc[i]; }
.LBB0_955:
	s_or_b64 exec, exec, s[8:9]
	v_ashrrev_i32_e32 v127, 5, v13
	v_mov_b32_e32 v17, 0
	v_cmp_lt_i32_e32 vcc, 0, v127
	v_mov_b32_e32 v16, 0
	v_mov_b32_e32 v15, 0
	v_mov_b32_e32 v14, 0
	v_mov_b32_e32 v13, 0
	v_mov_b32_e32 v12, 0
	v_mov_b32_e32 v11, 0
	v_mov_b32_e32 v10, 0
	v_mov_b32_e32 v9, 0
	v_mov_b32_e32 v8, 0
	v_mov_b32_e32 v7, 0
	v_mov_b32_e32 v6, 0
	v_mov_b32_e32 v5, 0
	v_mov_b32_e32 v4, 0
	v_mov_b32_e32 v3, 0
	v_mov_b32_e32 v2, 0
	v_mov_b32_e32 v33, 0
	v_mov_b32_e32 v32, 0
	v_mov_b32_e32 v31, 0
	v_mov_b32_e32 v30, 0
	v_mov_b32_e32 v29, 0
	v_mov_b32_e32 v28, 0
	v_mov_b32_e32 v27, 0
	v_mov_b32_e32 v26, 0
	v_mov_b32_e32 v25, 0
	v_mov_b32_e32 v24, 0
	v_mov_b32_e32 v23, 0
	v_mov_b32_e32 v22, 0
	v_mov_b32_e32 v21, 0
	v_mov_b32_e32 v20, 0
	v_mov_b32_e32 v19, 0
	v_mov_b32_e32 v18, 0
	v_mov_b32_e32 v153, 0
	s_and_saveexec_b64 s[8:9], vcc
	s_cbranch_execz .LBB0_961
	s_nop 0
	v_readfirstlane_b32 s2, v127
	s_mov_b64 s[10:11], 0
	v_lshl_add_u32 v154, v128, 2, v34
	v_lshl_add_u32 v155, v146, 2, v34
	ds_read_b32 v174, v154
	ds_read2_b32 v[176:177], v155 offset0:0 offset1:8
	ds_read2_b32 v[178:179], v155 offset0:16 offset1:24
	s_waitcnt lgkmcnt(0)
	v_and_b32_e32 v0, 0x1fff, v174
	v_or_b32_e32 v0, s0, v0
	v_lshlrev_b32_e32 v0, 8, v0
	v_lshl_add_u64 v[182:183], v[116:117], 0, v[0:1]
	global_load_dwordx4 v[170:173], v[182:183], off
	global_load_dwordx4 v[106:109], v[182:183], off offset:32
	global_load_dwordx4 v[102:105], v[182:183], off offset:64
	global_load_dwordx4 v[98:101], v[182:183], off offset:96
	v_and_b32_e32 v0, 0x1fff, v176
	v_or_b32_e32 v0, s0, v0
	v_lshlrev_b32_e32 v0, 8, v0
	v_lshl_add_u64 v[182:183], v[118:119], 0, v[0:1]
	global_load_dwordx4 v[78:81], v[182:183], off offset:128
	v_and_b32_e32 v0, 0x1fff, v177
	v_or_b32_e32 v0, s0, v0
	v_lshlrev_b32_e32 v0, 8, v0
	v_lshl_add_u64 v[182:183], v[118:119], 0, v[0:1]
	global_load_dwordx4 v[74:77], v[182:183], off offset:128
	v_and_b32_e32 v0, 0x1fff, v178
	v_or_b32_e32 v0, s0, v0
	v_lshlrev_b32_e32 v0, 8, v0
	v_lshl_add_u64 v[182:183], v[118:119], 0, v[0:1]
	global_load_dwordx4 v[70:73], v[182:183], off offset:128
	v_and_b32_e32 v0, 0x1fff, v179
	v_or_b32_e32 v0, s0, v0
	v_lshlrev_b32_e32 v0, 8, v0
	v_lshl_add_u64 v[182:183], v[118:119], 0, v[0:1]
	global_load_dwordx4 v[66:69], v[182:183], off offset:128
	ds_read_b32 v174, v154 offset:128
	ds_read2_b32 v[176:177], v155 offset0:32 offset1:40
	ds_read2_b32 v[178:179], v155 offset0:48 offset1:56
	s_waitcnt lgkmcnt(0)
	v_and_b32_e32 v0, 0x1fff, v174
	v_or_b32_e32 v0, s0, v0
	v_lshlrev_b32_e32 v0, 8, v0
	v_lshl_add_u64 v[182:183], v[116:117], 0, v[0:1]
	global_load_dwordx4 v[94:97], v[182:183], off
	global_load_dwordx4 v[90:93], v[182:183], off offset:32
	global_load_dwordx4 v[86:89], v[182:183], off offset:64
	global_load_dwordx4 v[82:85], v[182:183], off offset:96
	v_and_b32_e32 v0, 0x1fff, v176
	v_or_b32_e32 v0, s0, v0
	v_lshlrev_b32_e32 v0, 8, v0
	v_lshl_add_u64 v[182:183], v[118:119], 0, v[0:1]
	global_load_dwordx4 v[156:159], v[182:183], off offset:128
	v_and_b32_e32 v0, 0x1fff, v177
	v_or_b32_e32 v0, s0, v0
	v_lshlrev_b32_e32 v0, 8, v0
	v_lshl_add_u64 v[182:183], v[118:119], 0, v[0:1]
	global_load_dwordx4 v[160:163], v[182:183], off offset:128
	v_and_b32_e32 v0, 0x1fff, v178
	v_or_b32_e32 v0, s0, v0
	v_lshlrev_b32_e32 v0, 8, v0
	v_lshl_add_u64 v[182:183], v[118:119], 0, v[0:1]
	global_load_dwordx4 v[130:133], v[182:183], off offset:128
	v_and_b32_e32 v0, 0x1fff, v179
	v_or_b32_e32 v0, s0, v0
	v_lshlrev_b32_e32 v0, 8, v0
	v_lshl_add_u64 v[182:183], v[118:119], 0, v[0:1]
	global_load_dwordx4 v[134:137], v[182:183], off offset:128
	v_add_u32_e32 v154, 0x100, v154
	v_add_u32_e32 v155, 0x100, v155
	s_mov_b32 s3, 0
.Lmy_g_loop:
	s_add_i32 s12, s3, 2
	s_cmp_lt_u32 s12, s2
	s_cbranch_scc0 .Lmy_g_last
	s_waitcnt vmcnt(8)
	ds_write_b128 v151, v[78:81]
	ds_write_b128 v151, v[74:77] offset:1152
	ds_write_b128 v151, v[70:73] offset:2304
	ds_write_b128 v151, v[66:69] offset:3456
	v_mfma_f32_32x32x16_bf16 v[34:49], v[170:173], v[54:57], 0
	s_waitcnt lgkmcnt(0)
	v_mfma_f32_32x32x16_bf16 v[34:49], v[106:109], v[50:53], v[34:49]
	v_mfma_f32_32x32x16_bf16 v[34:49], v[102:105], v[62:65], v[34:49]
	v_mfma_f32_32x32x16_bf16 v[34:49], v[98:101], v[58:61], v[34:49]
	ds_read_b64_tr_b16 v[184:185], v152 offset:64
	ds_read_b64_tr_b16 v[186:187], v152 offset:1216
	ds_read_b32 v174, v154
	ds_read2_b32 v[176:177], v155 offset0:0 offset1:8
	ds_read2_b32 v[178:179], v155 offset0:16 offset1:24
	s_waitcnt lgkmcnt(0)
	v_and_b32_e32 v0, 0x1fff, v174
	v_or_b32_e32 v0, s0, v0
	v_lshlrev_b32_e32 v0, 8, v0
	v_lshl_add_u64 v[182:183], v[116:117], 0, v[0:1]
	global_load_dwordx4 v[170:173], v[182:183], off
	global_load_dwordx4 v[106:109], v[182:183], off offset:32
	global_load_dwordx4 v[102:105], v[182:183], off offset:64
	global_load_dwordx4 v[98:101], v[182:183], off offset:96
	v_and_b32_e32 v0, 0x1fff, v176
	v_or_b32_e32 v0, s0, v0
	v_lshlrev_b32_e32 v0, 8, v0
	v_lshl_add_u64 v[182:183], v[118:119], 0, v[0:1]
	global_load_dwordx4 v[78:81], v[182:183], off offset:128
	v_and_b32_e32 v0, 0x1fff, v177
	v_or_b32_e32 v0, s0, v0
	v_lshlrev_b32_e32 v0, 8, v0
	v_lshl_add_u64 v[182:183], v[118:119], 0, v[0:1]
	global_load_dwordx4 v[74:77], v[182:183], off offset:128
	v_and_b32_e32 v0, 0x1fff, v178
	v_or_b32_e32 v0, s0, v0
	v_lshlrev_b32_e32 v0, 8, v0
	v_lshl_add_u64 v[182:183], v[118:119], 0, v[0:1]
	global_load_dwordx4 v[70:73], v[182:183], off offset:128
	v_and_b32_e32 v0, 0x1fff, v179
	v_or_b32_e32 v0, s0, v0
	v_lshlrev_b32_e32 v0, 8, v0
	v_lshl_add_u64 v[182:183], v[118:119], 0, v[0:1]
	global_load_dwordx4 v[66:69], v[182:183], off offset:128
	v_exp_f32_e32 v34, v34
	v_exp_f32_e32 v35, v35
	v_exp_f32_e32 v36, v36
	v_exp_f32_e32 v37, v37
	v_exp_f32_e32 v38, v38
	v_exp_f32_e32 v39, v39
	v_exp_f32_e32 v40, v40
	v_exp_f32_e32 v41, v41
	v_add_f32_e32 v153, v153, v34
	v_add_f32_e32 v153, v153, v35
	v_add_f32_e32 v153, v153, v36
	v_add_f32_e32 v153, v153, v37
	v_add_f32_e32 v153, v153, v38
	v_add_f32_e32 v153, v153, v39
	v_add_f32_e32 v153, v153, v40
	v_add_f32_e32 v153, v153, v41
	v_cvt_pk_bf16_f32 v34, v34, v35
	v_cvt_pk_bf16_f32 v35, v36, v37
	v_cvt_pk_bf16_f32 v36, v38, v39
	v_cvt_pk_bf16_f32 v37, v40, v41
	ds_read_b64_tr_b16 v[38:39], v152
	ds_read_b64_tr_b16 v[40:41], v152 offset:1152
	v_exp_f32_e32 v42, v42
	v_exp_f32_e32 v43, v43
	v_exp_f32_e32 v44, v44
	v_exp_f32_e32 v45, v45
	v_exp_f32_e32 v46, v46
	v_exp_f32_e32 v47, v47
	v_exp_f32_e32 v48, v48
	v_exp_f32_e32 v49, v49
	s_waitcnt lgkmcnt(0)
; #define LAS __attribute__((address_space(3)))
; #define MFMA32(a, b, c) __builtin_amdgcn_mfma_f32_32x32x16_bf16((a), (b), (c), 0, 0, 0)
; DI float fexp2(float x) { return __builtin_amdgcn_exp2f(x); }
; DI f32x16 zero16() { f32x16 z; for (int i = 0; i < 16; ++i) z[i] = 0.f; return z; }
; DI void lds_wave_sync() { asm volatile("s_waitcnt lgkmcnt(0)" ::: "memory"); __builtin_amdgcn_wave_barrier(); asm volatile("" ::: "memory"); }
; DI void dsa_unit(const Params& p, int l, int b, int g32, LAS unsigned char* lds) {
;     ...
;     for (int mt = 0; mt < ntile; ++mt) {
;       bf16x8 a[4];
; #pragma unroll
;       for (int s = 0; s < 4; ++s) a[s] = __builtin_bit_cast(bf16x8, ka[s]);
; #pragma unroll
;       for (int u = 0; u < 4; ++u) *(LAS u32x4*)(vt + (8 * u + ks) * KT_RS + dg * 16) = va4[u];
;       if (mt + 1 < ntile) {
;         const unsigned ik = cq[32 * (mt + 1) + r] & 0x1FFFu; const u16* kp = kvc + ((size_t)b * S + ik) * 128 + 8 * h;
; #pragma unroll
;         for (int s = 0; s < 4; ++s) ka[s] = *(const u32x4*)(kp + 16 * s);
; #pragma unroll
;         for (int u = 0; u < 4; ++u) { const unsigned iv = cq[32 * (mt + 1) + 8 * u + ks] & 0x1FFFu; va4[u] = *(const u32x4*)(kvc + ((size_t)b * S + iv) * 128 + 64 + 8 * dg); }
;       }
;       f32x16 sc = zero16();
; #pragma unroll
;       for (int s = 0; s < 4; ++s) sc = MFMA32(a[s], qb[s], sc);
; #pragma unroll
;       for (int i = 0; i < 16; ++i) { sc[i] = fexp2(sc[i]); lsum += sc[i]; }
;       lds_wave_sync();
; #pragma unroll
;       for (int s = 0; s < 2; ++s) {
;         const bf16x8 pf = pack8(sc, s);
; #pragma unroll
;         for (int et = 0; et < 2; ++et) { const bf16x8 vf = vfrag144(vt, 16 * s + 4 * h, 32 * et, lane); o[et] = MFMA32(vf, pf, o[et]); }
;       }
;       lds_wave_sync();
;     }
	v_mfma_f32_32x32x16_bf16 v[18:33], v[38:41], v[34:37], v[18:33]
	ds_read_b64_tr_b16 v[38:39], v152 offset:2304
	ds_read_b64_tr_b16 v[40:41], v152 offset:3456
	v_mfma_f32_32x32x16_bf16 v[2:17], v[184:187], v[34:37], v[2:17]
	ds_read_b64_tr_b16 v[184:185], v152 offset:2368
	ds_read_b64_tr_b16 v[186:187], v152 offset:3520
	v_cvt_pk_bf16_f32 v34, v42, v43
	v_cvt_pk_bf16_f32 v35, v44, v45
	v_cvt_pk_bf16_f32 v36, v46, v47
	v_cvt_pk_bf16_f32 v37, v48, v49
	v_add_f32_e32 v153, v153, v42
	v_add_f32_e32 v153, v153, v43
	v_add_f32_e32 v153, v153, v44
	v_add_f32_e32 v153, v153, v45
	v_add_f32_e32 v153, v153, v46
	v_add_f32_e32 v153, v153, v47
	v_add_f32_e32 v153, v153, v48
	v_add_f32_e32 v153, v153, v49
	s_waitcnt lgkmcnt(2)
	v_mfma_f32_32x32x16_bf16 v[18:33], v[38:41], v[34:37], v[18:33]
	s_waitcnt lgkmcnt(0)
	v_mfma_f32_32x32x16_bf16 v[2:17], v[184:187], v[34:37], v[2:17]
	s_waitcnt vmcnt(8)
	ds_write_b128 v151, v[156:159]
	ds_write_b128 v151, v[160:163] offset:1152
	ds_write_b128 v151, v[130:133] offset:2304
	ds_write_b128 v151, v[134:137] offset:3456
	v_mfma_f32_32x32x16_bf16 v[34:49], v[94:97], v[54:57], 0
	s_waitcnt lgkmcnt(0)
	v_mfma_f32_32x32x16_bf16 v[34:49], v[90:93], v[50:53], v[34:49]
	v_mfma_f32_32x32x16_bf16 v[34:49], v[86:89], v[62:65], v[34:49]
	v_mfma_f32_32x32x16_bf16 v[34:49], v[82:85], v[58:61], v[34:49]
	ds_read_b64_tr_b16 v[184:185], v152 offset:64
	ds_read_b64_tr_b16 v[186:187], v152 offset:1216
	ds_read_b32 v174, v154 offset:128
	ds_read2_b32 v[176:177], v155 offset0:32 offset1:40
	ds_read2_b32 v[178:179], v155 offset0:48 offset1:56
	s_waitcnt lgkmcnt(0)
	v_and_b32_e32 v0, 0x1fff, v174
	v_or_b32_e32 v0, s0, v0
	v_lshlrev_b32_e32 v0, 8, v0
	v_lshl_add_u64 v[182:183], v[116:117], 0, v[0:1]
	global_load_dwordx4 v[94:97], v[182:183], off
	global_load_dwordx4 v[90:93], v[182:183], off offset:32
	global_load_dwordx4 v[86:89], v[182:183], off offset:64
	global_load_dwordx4 v[82:85], v[182:183], off offset:96
	v_and_b32_e32 v0, 0x1fff, v176
	v_or_b32_e32 v0, s0, v0
	v_lshlrev_b32_e32 v0, 8, v0
	v_lshl_add_u64 v[182:183], v[118:119], 0, v[0:1]
	global_load_dwordx4 v[156:159], v[182:183], off offset:128
	v_and_b32_e32 v0, 0x1fff, v177
	v_or_b32_e32 v0, s0, v0
	v_lshlrev_b32_e32 v0, 8, v0
	v_lshl_add_u64 v[182:183], v[118:119], 0, v[0:1]
	global_load_dwordx4 v[160:163], v[182:183], off offset:128
	v_and_b32_e32 v0, 0x1fff, v178
	v_or_b32_e32 v0, s0, v0
	v_lshlrev_b32_e32 v0, 8, v0
	v_lshl_add_u64 v[182:183], v[118:119], 0, v[0:1]
	global_load_dwordx4 v[130:133], v[182:183], off offset:128
	v_and_b32_e32 v0, 0x1fff, v179
	v_or_b32_e32 v0, s0, v0
	v_lshlrev_b32_e32 v0, 8, v0
	v_lshl_add_u64 v[182:183], v[118:119], 0, v[0:1]
	global_load_dwordx4 v[134:137], v[182:183], off offset:128
	v_exp_f32_e32 v34, v34
	v_exp_f32_e32 v35, v35
	v_exp_f32_e32 v36, v36
	v_exp_f32_e32 v37, v37
	v_exp_f32_e32 v38, v38
	v_exp_f32_e32 v39, v39
	v_exp_f32_e32 v40, v40
	v_exp_f32_e32 v41, v41
	v_add_f32_e32 v153, v153, v34
	v_add_f32_e32 v153, v153, v35
	v_add_f32_e32 v153, v153, v36
	v_add_f32_e32 v153, v153, v37
	v_add_f32_e32 v153, v153, v38
	v_add_f32_e32 v153, v153, v39
	v_add_f32_e32 v153, v153, v40
	v_add_f32_e32 v153, v153, v41
	v_cvt_pk_bf16_f32 v34, v34, v35
	v_cvt_pk_bf16_f32 v35, v36, v37
	v_cvt_pk_bf16_f32 v36, v38, v39
	v_cvt_pk_bf16_f32 v37, v40, v41
	ds_read_b64_tr_b16 v[38:39], v152
	ds_read_b64_tr_b16 v[40:41], v152 offset:1152
	v_exp_f32_e32 v42, v42
	v_exp_f32_e32 v43, v43
	v_exp_f32_e32 v44, v44
	v_exp_f32_e32 v45, v45
	v_exp_f32_e32 v46, v46
	v_exp_f32_e32 v47, v47
	v_exp_f32_e32 v48, v48
	v_exp_f32_e32 v49, v49
	s_waitcnt lgkmcnt(0)
	v_mfma_f32_32x32x16_bf16 v[18:33], v[38:41], v[34:37], v[18:33]
	ds_read_b64_tr_b16 v[38:39], v152 offset:2304
	ds_read_b64_tr_b16 v[40:41], v152 offset:3456
	v_mfma_f32_32x32x16_bf16 v[2:17], v[184:187], v[34:37], v[2:17]
	ds_read_b64_tr_b16 v[184:185], v152 offset:2368
	ds_read_b64_tr_b16 v[186:187], v152 offset:3520
	v_cvt_pk_bf16_f32 v34, v42, v43
	v_cvt_pk_bf16_f32 v35, v44, v45
	v_cvt_pk_bf16_f32 v36, v46, v47
	v_cvt_pk_bf16_f32 v37, v48, v49
	v_add_f32_e32 v153, v153, v42
	v_add_f32_e32 v153, v153, v43
	v_add_f32_e32 v153, v153, v44
	v_add_f32_e32 v153, v153, v45
	v_add_f32_e32 v153, v153, v46
	v_add_f32_e32 v153, v153, v47
	v_add_f32_e32 v153, v153, v48
	v_add_f32_e32 v153, v153, v49
	s_waitcnt lgkmcnt(2)
	v_mfma_f32_32x32x16_bf16 v[18:33], v[38:41], v[34:37], v[18:33]
	s_waitcnt lgkmcnt(0)
	v_mfma_f32_32x32x16_bf16 v[2:17], v[184:187], v[34:37], v[2:17]
	v_add_u32_e32 v154, 0x100, v154
	v_add_u32_e32 v155, 0x100, v155
	s_mov_b32 s3, s12
	s_branch .Lmy_g_loop
; #define LAS __attribute__((address_space(3)))
; #define MFMA32(a, b, c) __builtin_amdgcn_mfma_f32_32x32x16_bf16((a), (b), (c), 0, 0, 0)
; DI float fexp2(float x) { return __builtin_amdgcn_exp2f(x); }
; DI f32x16 zero16() { f32x16 z; for (int i = 0; i < 16; ++i) z[i] = 0.f; return z; }
; DI void lds_wave_sync() { asm volatile("s_waitcnt lgkmcnt(0)" ::: "memory"); __builtin_amdgcn_wave_barrier(); asm volatile("" ::: "memory"); }
; DI void dsa_unit(const Params& p, int l, int b, int g32, LAS unsigned char* lds) {
;     ...
;     for (int mt = 0; mt < ntile; ++mt) {
;       bf16x8 a[4];
; #pragma unroll
;       for (int s = 0; s < 4; ++s) a[s] = __builtin_bit_cast(bf16x8, ka[s]);
; #pragma unroll
;       for (int u = 0; u < 4; ++u) *(LAS u32x4*)(vt + (8 * u + ks) * KT_RS + dg * 16) = va4[u];
;       if (mt + 1 < ntile) {
;         const unsigned ik = cq[32 * (mt + 1) + r] & 0x1FFFu; const u16* kp = kvc + ((size_t)b * S + ik) * 128 + 8 * h;
; #pragma unroll
;         for (int s = 0; s < 4; ++s) ka[s] = *(const u32x4*)(kp + 16 * s);
; #pragma unroll
;         for (int u = 0; u < 4; ++u) { const unsigned iv = cq[32 * (mt + 1) + 8 * u + ks] & 0x1FFFu; va4[u] = *(const u32x4*)(kvc + ((size_t)b * S + iv) * 128 + 64 + 8 * dg); }
;       }
;       f32x16 sc = zero16();
; #pragma unroll
;       for (int s = 0; s < 4; ++s) sc = MFMA32(a[s], qb[s], sc);
; #pragma unroll
;       for (int i = 0; i < 16; ++i) { sc[i] = fexp2(sc[i]); lsum += sc[i]; }
;       lds_wave_sync();
; #pragma unroll
;       for (int s = 0; s < 2; ++s) {
;         const bf16x8 pf = pack8(sc, s);
; #pragma unroll
;         for (int et = 0; et < 2; ++et) { const bf16x8 vf = vfrag144(vt, 16 * s + 4 * h, 32 * et, lane); o[et] = MFMA32(vf, pf, o[et]); }
;       }
;       lds_wave_sync();
;     }
.Lmy_g_last:
	s_waitcnt vmcnt(8)
	ds_write_b128 v151, v[78:81]
	ds_write_b128 v151, v[74:77] offset:1152
	ds_write_b128 v151, v[70:73] offset:2304
	ds_write_b128 v151, v[66:69] offset:3456
	v_mfma_f32_32x32x16_bf16 v[34:49], v[170:173], v[54:57], 0
	s_waitcnt lgkmcnt(0)
	v_mfma_f32_32x32x16_bf16 v[34:49], v[106:109], v[50:53], v[34:49]
	v_mfma_f32_32x32x16_bf16 v[34:49], v[102:105], v[62:65], v[34:49]
	v_mfma_f32_32x32x16_bf16 v[34:49], v[98:101], v[58:61], v[34:49]
	ds_read_b64_tr_b16 v[184:185], v152 offset:64
	ds_read_b64_tr_b16 v[186:187], v152 offset:1216
	s_nop 11
	v_exp_f32_e32 v34, v34
	v_exp_f32_e32 v35, v35
	v_exp_f32_e32 v36, v36
	v_exp_f32_e32 v37, v37
	v_exp_f32_e32 v38, v38
	v_exp_f32_e32 v39, v39
	v_exp_f32_e32 v40, v40
	v_exp_f32_e32 v41, v41
	v_add_f32_e32 v153, v153, v34
	v_add_f32_e32 v153, v153, v35
	v_add_f32_e32 v153, v153, v36
	v_add_f32_e32 v153, v153, v37
	v_add_f32_e32 v153, v153, v38
	v_add_f32_e32 v153, v153, v39
	v_add_f32_e32 v153, v153, v40
	v_add_f32_e32 v153, v153, v41
	v_cvt_pk_bf16_f32 v34, v34, v35
	v_cvt_pk_bf16_f32 v35, v36, v37
	v_cvt_pk_bf16_f32 v36, v38, v39
	v_cvt_pk_bf16_f32 v37, v40, v41
	ds_read_b64_tr_b16 v[38:39], v152
	ds_read_b64_tr_b16 v[40:41], v152 offset:1152
	v_exp_f32_e32 v42, v42
	v_exp_f32_e32 v43, v43
	v_exp_f32_e32 v44, v44
	v_exp_f32_e32 v45, v45
	v_exp_f32_e32 v46, v46
	v_exp_f32_e32 v47, v47
	v_exp_f32_e32 v48, v48
	v_exp_f32_e32 v49, v49
	s_waitcnt lgkmcnt(0)
	v_mfma_f32_32x32x16_bf16 v[18:33], v[38:41], v[34:37], v[18:33]
	ds_read_b64_tr_b16 v[38:39], v152 offset:2304
	ds_read_b64_tr_b16 v[40:41], v152 offset:3456
	v_mfma_f32_32x32x16_bf16 v[2:17], v[184:187], v[34:37], v[2:17]
	ds_read_b64_tr_b16 v[184:185], v152 offset:2368
	ds_read_b64_tr_b16 v[186:187], v152 offset:3520
	v_cvt_pk_bf16_f32 v34, v42, v43
	v_cvt_pk_bf16_f32 v35, v44, v45
	v_cvt_pk_bf16_f32 v36, v46, v47
	v_cvt_pk_bf16_f32 v37, v48, v49
	v_add_f32_e32 v153, v153, v42
	v_add_f32_e32 v153, v153, v43
	v_add_f32_e32 v153, v153, v44
	v_add_f32_e32 v153, v153, v45
	v_add_f32_e32 v153, v153, v46
	v_add_f32_e32 v153, v153, v47
	v_add_f32_e32 v153, v153, v48
	v_add_f32_e32 v153, v153, v49
	s_waitcnt lgkmcnt(2)
	v_mfma_f32_32x32x16_bf16 v[18:33], v[38:41], v[34:37], v[18:33]
	s_waitcnt lgkmcnt(0)
	v_mfma_f32_32x32x16_bf16 v[2:17], v[184:187], v[34:37], v[2:17]
	s_waitcnt vmcnt(0)
	ds_write_b128 v151, v[156:159]
	ds_write_b128 v151, v[160:163] offset:1152
	ds_write_b128 v151, v[130:133] offset:2304
	ds_write_b128 v151, v[134:137] offset:3456
	v_mfma_f32_32x32x16_bf16 v[34:49], v[94:97], v[54:57], 0
	s_waitcnt lgkmcnt(0)
	v_mfma_f32_32x32x16_bf16 v[34:49], v[90:93], v[50:53], v[34:49]
	v_mfma_f32_32x32x16_bf16 v[34:49], v[86:89], v[62:65], v[34:49]
	v_mfma_f32_32x32x16_bf16 v[34:49], v[82:85], v[58:61], v[34:49]
	ds_read_b64_tr_b16 v[184:185], v152 offset:64
	ds_read_b64_tr_b16 v[186:187], v152 offset:1216
	s_nop 11
	v_exp_f32_e32 v34, v34
	v_exp_f32_e32 v35, v35
	v_exp_f32_e32 v36, v36
	v_exp_f32_e32 v37, v37
	v_exp_f32_e32 v38, v38
	v_exp_f32_e32 v39, v39
	v_exp_f32_e32 v40, v40
	v_exp_f32_e32 v41, v41
	v_add_f32_e32 v153, v153, v34
	v_add_f32_e32 v153, v153, v35
	v_add_f32_e32 v153, v153, v36
	v_add_f32_e32 v153, v153, v37
	v_add_f32_e32 v153, v153, v38
	v_add_f32_e32 v153, v153, v39
	v_add_f32_e32 v153, v153, v40
	v_add_f32_e32 v153, v153, v41
	v_cvt_pk_bf16_f32 v34, v34, v35
	v_cvt_pk_bf16_f32 v35, v36, v37
	v_cvt_pk_bf16_f32 v36, v38, v39
	v_cvt_pk_bf16_f32 v37, v40, v41
	ds_read_b64_tr_b16 v[38:39], v152
	ds_read_b64_tr_b16 v[40:41], v152 offset:1152
	v_exp_f32_e32 v42, v42
	v_exp_f32_e32 v43, v43
	v_exp_f32_e32 v44, v44
	v_exp_f32_e32 v45, v45
	v_exp_f32_e32 v46, v46
	v_exp_f32_e32 v47, v47
	v_exp_f32_e32 v48, v48
	v_exp_f32_e32 v49, v49
	s_waitcnt lgkmcnt(0)
	v_mfma_f32_32x32x16_bf16 v[18:33], v[38:41], v[34:37], v[18:33]
	ds_read_b64_tr_b16 v[38:39], v152 offset:2304
	ds_read_b64_tr_b16 v[40:41], v152 offset:3456
	v_mfma_f32_32x32x16_bf16 v[2:17], v[184:187], v[34:37], v[2:17]
	ds_read_b64_tr_b16 v[184:185], v152 offset:2368
	ds_read_b64_tr_b16 v[186:187], v152 offset:3520
	v_cvt_pk_bf16_f32 v34, v42, v43
	v_cvt_pk_bf16_f32 v35, v44, v45
	v_cvt_pk_bf16_f32 v36, v46, v47
	v_cvt_pk_bf16_f32 v37, v48, v49
	v_add_f32_e32 v153, v153, v42
	v_add_f32_e32 v153, v153, v43
	v_add_f32_e32 v153, v153, v44
	v_add_f32_e32 v153, v153, v45
	v_add_f32_e32 v153, v153, v46
	v_add_f32_e32 v153, v153, v47
	v_add_f32_e32 v153, v153, v48
	v_add_f32_e32 v153, v153, v49
	s_waitcnt lgkmcnt(2)
	v_mfma_f32_32x32x16_bf16 v[18:33], v[38:41], v[34:37], v[18:33]
	s_waitcnt lgkmcnt(0)
	v_mfma_f32_32x32x16_bf16 v[2:17], v[184:187], v[34:37], v[2:17]

; DI void dsa_unit(const Params& p, int l, int b, int g32, LAS unsigned char* lds) {
;     ...
;   }
;   __syncthreads();
; }
.LBB0_1000:
	v_mov_b64_e32 v[130:131], 0x1100
	v_mov_b64_e32 v[132:133], 0x10ff
	v_mov_b64_e32 v[134:135], 0x400
	v_mov_b64_e32 v[136:137], 0x3ff
	v_mov_b32_e32 v170, 0x358637bd
	v_mov_b32_e32 v171, 0x3e91f4c4
	v_mov_b32_e32 v172, 0x3c0881c4
	v_mov_b32_e32 v173, 0xbab64f3b
	v_mov_b32_e32 v174, 0x3ecc95a3
	v_mov_b32_e32 v176, 0x37000000
	v_mov_b32_e32 v177, 0x7f800000
	v_not_b32_e32 v178, 63
	v_not_b32_e32 v179, 31
	v_mov_b32_e32 v182, 0x42800000
	v_mov_b32_e32 v183, 0xff800000
	v_mov_b32_e32 v184, 0x3eb60549
	v_mov_b32_e32 v185, 0x3e4ccccd
	v_mov_b32_e32 v186, 0x42000000
	v_mov_b32_e32 v187, 0xc2800000
	s_waitcnt lgkmcnt(0)
	s_barrier
	s_cbranch_execz .LBB0_965
	s_branch .LBB0_977
